# v58 + windowed-attention unit epilogues: 8 dwordx2 stores -> permlane32_swap pairs + 4 dwordx4 stores
# speedup vs baseline: 1.0119x; 1.0119x over previous
; __device__ __forceinline__ unsigned pk_bf16(float lo, float hi) { f32x2 v = {lo, hi}; bf16x2_t b = __builtin_convertvector(v, bf16x2_t); return __builtin_bit_cast(unsigned, b); }
; template <int MODE> ...
;     ...
;     bf16* orow = Ob + (size_t)qtok * 1024 + 4 * hi;
; #pragma unroll
;     for (int gq = 0; gq < 4; ++gq) {
;         v2u w; w.x = pk_bf16(o0[4 * gq] * inv, o0[4 * gq + 1] * inv); w.y = pk_bf16(o0[4 * gq + 2] * inv, o0[4 * gq + 3] * inv); *(v2u*)(orow + 8 * gq) = w;
;         v2u w2; w2.x = pk_bf16(o1[4 * gq] * inv, o1[4 * gq + 1] * inv); w2.y = pk_bf16(o1[4 * gq + 2] * inv, o1[4 * gq + 3] * inv); *(v2u*)(orow + 32 + 8 * gq) = w2;
;     }
.LBB0_463:
	s_or_b64 exec, exec, s[0:1]
	s_lshl_b64 s[0:1], s[40:41], 25
	s_add_u32 s0, s89, s0
	s_addc_u32 s1, s93, s1
	s_add_u32 s0, s0, s42
	s_addc_u32 s1, s1, s43
	v_lshlrev_b64 v[32:33], 11, v[124:125]
	v_lshl_add_u64 v[32:33], s[0:1], 0, v[32:33]
	v_lshlrev_b32_e32 v128, 1, v116
	v_lshl_add_u64 v[32:33], v[32:33], 0, v[128:129]
	v_lshl_add_u64 v[32:33], v[32:33], 0, v[128:129]
	v_cvt_pk_bf16_f32 v36, v2, v3
	v_cvt_pk_bf16_f32 v37, v8, v9
	s_add_i32 s29, s29, s94
	v_cvt_pk_bf16_f32 v38, v10, v11
	v_cvt_pk_bf16_f32 v39, v16, v17
	v_cvt_pk_bf16_f32 v40, v18, v19
	v_cvt_pk_bf16_f32 v41, v24, v25
	v_cvt_pk_bf16_f32 v42, v26, v27
	v_cvt_pk_bf16_f32 v43, v30, v31
	v_cvt_pk_bf16_f32 v44, v0, v1
	v_cvt_pk_bf16_f32 v45, v4, v5
	v_cvt_pk_bf16_f32 v46, v6, v7
	v_cvt_pk_bf16_f32 v47, v12, v13
	v_cvt_pk_bf16_f32 v48, v14, v15
	v_cvt_pk_bf16_f32 v49, v20, v21
	v_cvt_pk_bf16_f32 v50, v22, v23
	v_cvt_pk_bf16_f32 v51, v28, v29
	s_cmpk_gt_i32 s29, 0x2ff
	s_nop 1
	v_permlane32_swap_b32_e32 v36, v38
	v_permlane32_swap_b32_e32 v37, v39
	v_permlane32_swap_b32_e32 v40, v42
	v_permlane32_swap_b32_e32 v41, v43
	v_permlane32_swap_b32_e32 v44, v46
	v_permlane32_swap_b32_e32 v45, v47
	v_permlane32_swap_b32_e32 v48, v50
	v_permlane32_swap_b32_e32 v49, v51
	global_store_dwordx4 v[32:33], v[36:39], off offset:512
	global_store_dwordx4 v[32:33], v[40:43], off offset:544
	global_store_dwordx4 v[32:33], v[44:47], off offset:576
	global_store_dwordx4 v[32:33], v[48:51], off offset:608
	s_cbranch_scc1 .LBB0_592

; __device__ __forceinline__ unsigned pk_bf16(float lo, float hi) { f32x2 v = {lo, hi}; bf16x2_t b = __builtin_convertvector(v, bf16x2_t); return __builtin_bit_cast(unsigned, b); }
; template <int MODE> ...
;     ...
;     bf16* orow = Ob + (size_t)qtok * 1024 + 4 * hi;
; #pragma unroll
;     for (int gq = 0; gq < 4; ++gq) {
;         v2u w; w.x = pk_bf16(o0[4 * gq] * inv, o0[4 * gq + 1] * inv); w.y = pk_bf16(o0[4 * gq + 2] * inv, o0[4 * gq + 3] * inv); *(v2u*)(orow + 8 * gq) = w;
;         v2u w2; w2.x = pk_bf16(o1[4 * gq] * inv, o1[4 * gq + 1] * inv); w2.y = pk_bf16(o1[4 * gq + 2] * inv, o1[4 * gq + 3] * inv); *(v2u*)(orow + 32 + 8 * gq) = w2;
;     }
.LBB0_594:
	s_or_b64 exec, exec, s[0:1]
	s_lshl_b32 s0, s20, 11
	s_add_u32 s0, s89, s0
	s_addc_u32 s1, s93, 0
	s_lshl_b32 s4, s21, 1
	s_add_u32 s0, s0, s4
	s_addc_u32 s1, s1, 0
	v_lshlrev_b64 v[32:33], 11, v[116:117]
	v_lshl_add_u64 v[32:33], s[0:1], 0, v[32:33]
	v_lshl_add_u64 v[32:33], v[32:33], 0, v[128:129]
	v_lshl_add_u64 v[32:33], v[32:33], 0, v[128:129]
	v_cvt_pk_bf16_f32 v36, v2, v3
	v_cvt_pk_bf16_f32 v37, v8, v9
	v_readlane_b32 s0, v255, 3
	v_cvt_pk_bf16_f32 v38, v10, v11
	v_cvt_pk_bf16_f32 v39, v16, v17
	s_add_i32 s14, s14, s0
	v_cvt_pk_bf16_f32 v40, v18, v19
	v_cvt_pk_bf16_f32 v41, v24, v25
	v_readlane_b32 s0, v255, 5
	v_cvt_pk_bf16_f32 v42, v26, v27
	v_cvt_pk_bf16_f32 v43, v30, v31
	s_add_i32 s15, s15, s94
	v_cvt_pk_bf16_f32 v44, v0, v1
	v_cvt_pk_bf16_f32 v45, v4, v5
	s_add_i32 s11, s11, s0
	v_cvt_pk_bf16_f32 v46, v6, v7
	v_cvt_pk_bf16_f32 v47, v12, v13
	v_cvt_pk_bf16_f32 v48, v14, v15
	v_cvt_pk_bf16_f32 v49, v20, v21
	v_cvt_pk_bf16_f32 v50, v22, v23
	v_cvt_pk_bf16_f32 v51, v28, v29
	s_cmpk_gt_i32 s15, 0x1ff
	s_nop 1
	v_permlane32_swap_b32_e32 v36, v38
	v_permlane32_swap_b32_e32 v37, v39
	v_permlane32_swap_b32_e32 v40, v42
	v_permlane32_swap_b32_e32 v41, v43
	v_permlane32_swap_b32_e32 v44, v46
	v_permlane32_swap_b32_e32 v45, v47
	v_permlane32_swap_b32_e32 v48, v50
	v_permlane32_swap_b32_e32 v49, v51
	global_store_dwordx4 v[32:33], v[36:39], off
	global_store_dwordx4 v[32:33], v[40:43], off offset:32
	global_store_dwordx4 v[32:33], v[44:47], off offset:64
	global_store_dwordx4 v[32:33], v[48:51], off offset:96
	s_cbranch_scc1 .LBB0_712
